# idx_scan threshold search: 16 serialized LDS word reads replaced by register moves (words already loaded / one reload); on top of sparse far + diff LUT
# baseline (speedup 1.0000x reference)
; DI void idx_scan(const u32* hq, int need, u32* outbin, u32* outneed, int q, int lane) {
;   u32 c = 0;
; #pragma unroll
;   for (int w = 0; w < 8; ++w) { u32 v = hq[8 * lane + w]; c += (v & 0xffffu) + (v >> 16); }
;   u32 incl = c;
; #pragma unroll
;   for (int o = 1; o < 64; o <<= 1) { u32 v = __shfl_down(incl, o); if (lane + o < 64) incl += v; }
;   const u32 above = incl - c;
;   if ((int)above < need && need <= (int)incl) {
;     u32 cum = above;
;     ...
;       u32 cnt = (hq[bin >> 1] >> ((bin & 1) * 16)) & 0xffffu;
;       if ((int)(cum + cnt) >= need) { outbin[q] = (u32)bin; outneed[q] = (u32)need - cum; break; }
;       cum += cnt;
;     }
;   }
; DI void idx_job(const Params& p, int b, int qg, unsigned char* smem) {
;     ...
;   for (int qq = 0; qq < 4; ++qq) idx_scan(hist + (wave * 4 + qq) * 512, 256, binA, needB, wave * 4 + qq, lane);
.LBB0_409:
	s_or_b64 exec, exec, s[2:3]
	s_waitcnt vmcnt(1)
	v_and_b32_e32 v43, 63, v207
	v_cmp_ne_u32_e64 s[4:5], 63, v43
	v_lshl_add_u32 v140, v109, 13, v96
	v_lshl_add_u32 v139, v141, 5, v140
	v_addc_co_u32_e64 v44, s[4:5], 0, v207, s[4:5]
	s_waitcnt lgkmcnt(0)
	s_barrier
	v_cmp_gt_u32_e64 s[4:5], 62, v43
	s_waitcnt vmcnt(0)
	ds_read_b128 v[48:51], v139
	ds_read_b128 v[52:55], v139 offset:16
	v_lshlrev_b32_e32 v130, 2, v44
	v_cndmask_b32_e64 v44, 0, 2, s[4:5]
	v_cmp_gt_u32_e64 s[4:5], 60, v43
	v_add_lshl_u32 v131, v44, v207, 2
	s_waitcnt lgkmcnt(1)
	v_lshrrev_b32_e32 v45, 16, v49
	v_cndmask_b32_e64 v44, 0, 4, s[4:5]
	v_cmp_gt_u32_e64 s[4:5], 56, v43
	v_add_lshl_u32 v132, v44, v207, 2
	v_cmp_eq_u32_e64 s[40:41], 63, v141
	v_cndmask_b32_e64 v44, 0, 8, s[4:5]
	v_cmp_gt_u32_e64 s[4:5], 48, v43
	v_add_lshl_u32 v133, v44, v207, 2
	v_and_b32_e32 v44, 0xffff, v49
	v_cndmask_b32_e64 v43, 0, 16, s[4:5]
	v_add_lshl_u32 v135, v43, v207, 2
	v_add_u32_sdwa v43, v48, v48 dst_sel:DWORD dst_unused:UNUSED_PAD src0_sel:WORD_1 src1_sel:WORD_0
	v_add3_u32 v43, v43, v45, v44
	v_and_b32_e32 v44, 0xffff, v50
	v_lshrrev_b32_e32 v45, 16, v50
	v_add3_u32 v43, v43, v45, v44
	v_and_b32_e32 v44, 0xffff, v51
	v_lshrrev_b32_e32 v45, 16, v51
	v_add3_u32 v43, v43, v45, v44
	s_waitcnt lgkmcnt(0)
	v_and_b32_e32 v44, 0xffff, v52
	v_lshrrev_b32_e32 v45, 16, v52
	v_add3_u32 v43, v43, v45, v44
	v_and_b32_e32 v44, 0xffff, v53
	v_lshrrev_b32_e32 v45, 16, v53
	v_add3_u32 v43, v43, v45, v44
	v_and_b32_e32 v44, 0xffff, v54
	v_lshrrev_b32_e32 v45, 16, v54
	v_add3_u32 v43, v43, v45, v44
	v_and_b32_e32 v44, 0xffff, v55
	v_lshrrev_b32_e32 v45, 16, v55
	v_add3_u32 v43, v43, v45, v44
	ds_bpermute_b32 v44, v130, v43
	v_cmp_gt_u32_e64 s[42:43], 62, v141
	v_cmp_gt_u32_e64 s[44:45], 60, v141
	v_cmp_gt_u32_e64 s[46:47], 56, v141
	v_cmp_gt_u32_e64 s[48:49], 48, v141
	s_waitcnt lgkmcnt(0)
	v_cndmask_b32_e64 v44, v44, 0, s[40:41]
	v_add_u32_e32 v44, v43, v44
	ds_bpermute_b32 v45, v131, v44
	v_lshl_or_b32 v134, v207, 2, v209
	v_cmp_gt_u32_e64 s[50:51], 32, v141
	v_lshlrev_b32_e32 v99, 4, v141
	s_movk_i32 s2, 0x100
	s_waitcnt lgkmcnt(0)
	v_cndmask_b32_e64 v45, 0, v45, s[42:43]
	v_add_u32_e32 v44, v44, v45
	ds_bpermute_b32 v45, v132, v44
	v_or_b32_e32 v129, 15, v99
	v_lshlrev_b32_e32 v42, 2, v109
	v_lshrrev_b32_e32 v46, 1, v129
	v_or_b32_e32 v127, 14, v99
	s_waitcnt lgkmcnt(0)
	v_cndmask_b32_e64 v45, 0, v45, s[44:45]
	v_add_u32_e32 v44, v44, v45
	ds_bpermute_b32 v45, v133, v44
	v_or_b32_e32 v125, 13, v99
	v_or_b32_e32 v120, 12, v99
	v_or_b32_e32 v121, 11, v99
	v_or_b32_e32 v117, 10, v99
	s_waitcnt lgkmcnt(0)
	v_cndmask_b32_e64 v45, 0, v45, s[46:47]
	v_add_u32_e32 v44, v44, v45
	ds_bpermute_b32 v45, v135, v44
	v_or_b32_e32 v118, 9, v99
	v_or_b32_e32 v115, 8, v99
	v_or_b32_e32 v113, 7, v99
	v_or_b32_e32 v111, 6, v99
	s_waitcnt lgkmcnt(0)
	v_cndmask_b32_e64 v45, 0, v45, s[48:49]
	v_add_u32_e32 v44, v44, v45
	ds_bpermute_b32 v45, v134, v44
	v_or_b32_e32 v107, 5, v99
	v_or_b32_e32 v105, 4, v99
	v_or_b32_e32 v103, 3, v99
	v_or_b32_e32 v101, 2, v99
	s_waitcnt lgkmcnt(0)
	v_cndmask_b32_e64 v45, 0, v45, s[50:51]
	v_add_u32_e32 v45, v44, v45
	v_sub_u32_e32 v44, v45, v43
	v_cmp_gt_i32_e64 s[4:5], s2, v44
	s_movk_i32 s2, 0xff
	v_cmp_lt_i32_e64 s[6:7], s2, v45
	v_lshrrev_b32_e32 v128, 1, v127
	v_lshrrev_b32_e32 v126, 1, v125
	v_lshrrev_b32_e32 v122, 1, v120
	v_lshrrev_b32_e32 v123, 1, v121
	v_lshrrev_b32_e32 v124, 1, v117
	v_lshrrev_b32_e32 v119, 1, v118
	v_lshrrev_b32_e32 v116, 1, v115
	v_lshrrev_b32_e32 v114, 1, v113
	v_lshrrev_b32_e32 v112, 1, v111
	v_lshrrev_b32_e32 v110, 1, v107
	v_lshrrev_b32_e32 v106, 1, v105
	v_lshrrev_b32_e32 v104, 1, v103
	v_lshrrev_b32_e32 v102, 1, v101
	v_or_b32_e32 v100, 1, v99
	s_and_b64 s[4:5], s[6:7], s[4:5]
	v_lshl_add_u32 v138, v42, 2, v96
	v_lshl_add_u32 v144, v46, 2, v140
	s_and_saveexec_b64 s[2:3], s[4:5]
	s_cbranch_execz .LBB0_458
	v_mov_b32_e32 v43, v55
	s_movk_i32 s4, 0x100
	s_movk_i32 s6, 0xff
	v_add_u32_sdwa v43, v43, v44 dst_sel:DWORD dst_unused:UNUSED_PAD src0_sel:WORD_1 src1_sel:DWORD
	v_cmp_gt_i32_e64 s[4:5], s4, v43
	v_cmp_lt_i32_e64 s[6:7], s6, v43
	s_and_saveexec_b64 s[8:9], s[6:7]
	v_sub_u32_e32 v43, 0x100, v44
	v_add_u32_e32 v45, 0xc000, v138
	ds_write2_b32 v45, v129, v43 offset0:80 offset1:96
	v_mov_b32_e32 v43, v44
	s_or_b64 exec, exec, s[8:9]
	s_and_saveexec_b64 s[6:7], s[4:5]
	s_xor_b64 s[6:7], exec, s[6:7]
	s_cbranch_execz .LBB0_458
	v_lshl_add_u32 v44, v128, 2, v140
	v_mov_b32_e32 v44, v55
	s_movk_i32 s4, 0x100
	s_movk_i32 s6, 0xff
	v_add_u32_sdwa v44, v44, v43 dst_sel:DWORD dst_unused:UNUSED_PAD src0_sel:WORD_0 src1_sel:DWORD
	v_cmp_gt_i32_e64 s[4:5], s4, v44
	v_cmp_lt_i32_e64 s[6:7], s6, v44
	s_and_saveexec_b64 s[8:9], s[6:7]
	v_sub_u32_e32 v44, 0x100, v43
	v_add_u32_e32 v45, 0xc000, v138
	ds_write2_b32 v45, v127, v44 offset0:80 offset1:96
	v_mov_b32_e32 v44, v43
	s_or_b64 exec, exec, s[8:9]
	s_and_saveexec_b64 s[8:9], s[4:5]
	s_cbranch_execz .LBB0_457
	v_lshl_add_u32 v43, v126, 2, v140
	v_mov_b32_e32 v43, v54
	s_movk_i32 s4, 0x100
	s_movk_i32 s6, 0xff
	v_add_u32_sdwa v43, v43, v44 dst_sel:DWORD dst_unused:UNUSED_PAD src0_sel:WORD_1 src1_sel:DWORD
	v_cmp_gt_i32_e64 s[4:5], s4, v43
	v_cmp_lt_i32_e64 s[6:7], s6, v43
	s_and_saveexec_b64 s[28:29], s[6:7]
	v_sub_u32_e32 v43, 0x100, v44
	v_add_u32_e32 v45, 0xc000, v138
	ds_write2_b32 v45, v125, v43 offset0:80 offset1:96
	v_mov_b32_e32 v43, v44
	s_or_b64 exec, exec, s[28:29]
	s_and_b64 exec, exec, s[4:5]
	s_cbranch_execz .LBB0_457
; DI void idx_scan(const u32* hq, int need, u32* outbin, u32* outneed, int q, int lane) {
;     ...
;   if ((int)above < need && need <= (int)incl) {
;     u32 cum = above;
;     ...
;       u32 cnt = (hq[bin >> 1] >> ((bin & 1) * 16)) & 0xffffu;
;       if ((int)(cum + cnt) >= need) { outbin[q] = (u32)bin; outneed[q] = (u32)need - cum; break; }
;       cum += cnt;
;     }
;   }
	v_lshl_add_u32 v44, v122, 2, v140
	v_mov_b32_e32 v44, v54
	s_movk_i32 s4, 0x100
	s_movk_i32 s6, 0xff
	v_add_u32_sdwa v44, v44, v43 dst_sel:DWORD dst_unused:UNUSED_PAD src0_sel:WORD_0 src1_sel:DWORD
	v_cmp_gt_i32_e64 s[4:5], s4, v44
	v_cmp_lt_i32_e64 s[6:7], s6, v44
	s_and_saveexec_b64 s[28:29], s[6:7]
	v_sub_u32_e32 v44, 0x100, v43
	v_add_u32_e32 v45, 0xc000, v138
	ds_write2_b32 v45, v120, v44 offset0:80 offset1:96
	v_mov_b32_e32 v44, v43
	s_or_b64 exec, exec, s[28:29]
	s_and_b64 exec, exec, s[4:5]
	s_cbranch_execz .LBB0_457
	v_lshl_add_u32 v43, v123, 2, v140
	v_mov_b32_e32 v43, v53
	s_movk_i32 s4, 0x100
	s_movk_i32 s6, 0xff
	v_add_u32_sdwa v43, v43, v44 dst_sel:DWORD dst_unused:UNUSED_PAD src0_sel:WORD_1 src1_sel:DWORD
	v_cmp_gt_i32_e64 s[4:5], s4, v43
	v_cmp_lt_i32_e64 s[6:7], s6, v43
	s_and_saveexec_b64 s[28:29], s[6:7]
	v_sub_u32_e32 v43, 0x100, v44
	v_add_u32_e32 v45, 0xc000, v138
	ds_write2_b32 v45, v121, v43 offset0:80 offset1:96
	v_mov_b32_e32 v43, v44
	s_or_b64 exec, exec, s[28:29]
	s_and_b64 exec, exec, s[4:5]
	s_cbranch_execz .LBB0_457
	v_lshl_add_u32 v44, v124, 2, v140
	v_mov_b32_e32 v44, v53
	s_movk_i32 s4, 0x100
	s_movk_i32 s6, 0xff
	v_add_u32_sdwa v44, v44, v43 dst_sel:DWORD dst_unused:UNUSED_PAD src0_sel:WORD_0 src1_sel:DWORD
	v_cmp_gt_i32_e64 s[4:5], s4, v44
	v_cmp_lt_i32_e64 s[6:7], s6, v44
	s_and_saveexec_b64 s[28:29], s[6:7]
	v_sub_u32_e32 v44, 0x100, v43
	v_add_u32_e32 v45, 0xc000, v138
	ds_write2_b32 v45, v117, v44 offset0:80 offset1:96
	v_mov_b32_e32 v44, v43
	s_or_b64 exec, exec, s[28:29]
	s_and_b64 exec, exec, s[4:5]
	s_cbranch_execz .LBB0_457
	v_lshl_add_u32 v43, v119, 2, v140
	v_mov_b32_e32 v43, v52
	s_movk_i32 s4, 0x100
	s_movk_i32 s6, 0xff
	v_add_u32_sdwa v43, v43, v44 dst_sel:DWORD dst_unused:UNUSED_PAD src0_sel:WORD_1 src1_sel:DWORD
	v_cmp_gt_i32_e64 s[4:5], s4, v43
	v_cmp_lt_i32_e64 s[6:7], s6, v43
	s_and_saveexec_b64 s[28:29], s[6:7]
	v_sub_u32_e32 v43, 0x100, v44
	v_add_u32_e32 v45, 0xc000, v138
	ds_write2_b32 v45, v118, v43 offset0:80 offset1:96
	v_mov_b32_e32 v43, v44
	s_or_b64 exec, exec, s[28:29]
	s_and_b64 exec, exec, s[4:5]
	s_cbranch_execz .LBB0_457
	v_lshl_add_u32 v44, v116, 2, v140
	v_mov_b32_e32 v44, v52
	s_movk_i32 s4, 0x100
	s_movk_i32 s6, 0xff
	v_add_u32_sdwa v44, v44, v43 dst_sel:DWORD dst_unused:UNUSED_PAD src0_sel:WORD_0 src1_sel:DWORD
	v_cmp_gt_i32_e64 s[4:5], s4, v44
	v_cmp_lt_i32_e64 s[6:7], s6, v44
	s_and_saveexec_b64 s[28:29], s[6:7]
	v_sub_u32_e32 v44, 0x100, v43
	v_add_u32_e32 v45, 0xc000, v138
	ds_write2_b32 v45, v115, v44 offset0:80 offset1:96
	v_mov_b32_e32 v44, v43
	s_or_b64 exec, exec, s[28:29]
	s_and_b64 exec, exec, s[4:5]
	s_cbranch_execz .LBB0_457
	v_lshl_add_u32 v43, v114, 2, v140
	v_mov_b32_e32 v43, v51
	s_movk_i32 s4, 0x100
	s_movk_i32 s6, 0xff
	v_add_u32_sdwa v43, v43, v44 dst_sel:DWORD dst_unused:UNUSED_PAD src0_sel:WORD_1 src1_sel:DWORD
	v_cmp_gt_i32_e64 s[4:5], s4, v43
	v_cmp_lt_i32_e64 s[6:7], s6, v43
	s_and_saveexec_b64 s[28:29], s[6:7]
	v_sub_u32_e32 v43, 0x100, v44
	v_add_u32_e32 v45, 0xc000, v138
	ds_write2_b32 v45, v113, v43 offset0:80 offset1:96
	v_mov_b32_e32 v43, v44
	s_or_b64 exec, exec, s[28:29]
	s_and_b64 exec, exec, s[4:5]
	s_cbranch_execz .LBB0_457
	v_lshl_add_u32 v44, v112, 2, v140
	v_mov_b32_e32 v44, v51
	s_movk_i32 s4, 0x100
	s_movk_i32 s6, 0xff
	v_add_u32_sdwa v44, v44, v43 dst_sel:DWORD dst_unused:UNUSED_PAD src0_sel:WORD_0 src1_sel:DWORD
	v_cmp_gt_i32_e64 s[4:5], s4, v44
	v_cmp_lt_i32_e64 s[6:7], s6, v44
	s_and_saveexec_b64 s[28:29], s[6:7]
	v_sub_u32_e32 v44, 0x100, v43
	v_add_u32_e32 v45, 0xc000, v138
	ds_write2_b32 v45, v111, v44 offset0:80 offset1:96
	v_mov_b32_e32 v44, v43
	s_or_b64 exec, exec, s[28:29]
	s_and_b64 exec, exec, s[4:5]
	s_cbranch_execz .LBB0_457
	v_lshl_add_u32 v43, v110, 2, v140
	v_mov_b32_e32 v43, v50
	s_movk_i32 s4, 0x100
	s_movk_i32 s6, 0xff
	v_add_u32_sdwa v43, v43, v44 dst_sel:DWORD dst_unused:UNUSED_PAD src0_sel:WORD_1 src1_sel:DWORD
	v_cmp_gt_i32_e64 s[4:5], s4, v43
	v_cmp_lt_i32_e64 s[6:7], s6, v43
	s_and_saveexec_b64 s[28:29], s[6:7]
	v_sub_u32_e32 v43, 0x100, v44
	v_add_u32_e32 v45, 0xc000, v138
	ds_write2_b32 v45, v107, v43 offset0:80 offset1:96
	v_mov_b32_e32 v43, v44
	s_or_b64 exec, exec, s[28:29]
	s_and_b64 exec, exec, s[4:5]
	s_cbranch_execz .LBB0_457
	v_lshl_add_u32 v44, v106, 2, v140
	v_mov_b32_e32 v44, v50
	s_movk_i32 s4, 0x100
	s_movk_i32 s6, 0xff
	v_add_u32_sdwa v44, v44, v43 dst_sel:DWORD dst_unused:UNUSED_PAD src0_sel:WORD_0 src1_sel:DWORD
	v_cmp_gt_i32_e64 s[4:5], s4, v44
	v_cmp_lt_i32_e64 s[6:7], s6, v44
	s_and_saveexec_b64 s[28:29], s[6:7]
	v_sub_u32_e32 v44, 0x100, v43
	v_add_u32_e32 v45, 0xc000, v138
	ds_write2_b32 v45, v105, v44 offset0:80 offset1:96
	v_mov_b32_e32 v44, v43
	s_or_b64 exec, exec, s[28:29]
	s_and_b64 exec, exec, s[4:5]
	s_cbranch_execz .LBB0_457
	v_lshl_add_u32 v43, v104, 2, v140
	v_mov_b32_e32 v43, v49
	s_movk_i32 s4, 0x100
	s_movk_i32 s6, 0xff
	v_add_u32_sdwa v43, v43, v44 dst_sel:DWORD dst_unused:UNUSED_PAD src0_sel:WORD_1 src1_sel:DWORD
	v_cmp_gt_i32_e64 s[4:5], s4, v43
	v_cmp_lt_i32_e64 s[6:7], s6, v43
	s_and_saveexec_b64 s[28:29], s[6:7]
	v_sub_u32_e32 v43, 0x100, v44
	v_add_u32_e32 v45, 0xc000, v138
	ds_write2_b32 v45, v103, v43 offset0:80 offset1:96
	v_mov_b32_e32 v43, v44
	s_or_b64 exec, exec, s[28:29]
	s_and_b64 exec, exec, s[4:5]
	s_cbranch_execz .LBB0_457
	v_lshl_add_u32 v44, v102, 2, v140
	v_mov_b32_e32 v44, v49
	s_movk_i32 s4, 0x100
	s_movk_i32 s6, 0xff
	v_add_u32_sdwa v44, v44, v43 dst_sel:DWORD dst_unused:UNUSED_PAD src0_sel:WORD_0 src1_sel:DWORD
	v_cmp_gt_i32_e64 s[4:5], s4, v44
	v_cmp_lt_i32_e64 s[6:7], s6, v44
	s_and_saveexec_b64 s[28:29], s[6:7]
	v_sub_u32_e32 v44, 0x100, v43
	v_add_u32_e32 v45, 0xc000, v138
	ds_write2_b32 v45, v101, v44 offset0:80 offset1:96
	v_mov_b32_e32 v44, v43
	s_or_b64 exec, exec, s[28:29]
	s_and_b64 exec, exec, s[4:5]
	s_cbranch_execz .LBB0_457
	v_mov_b32_e32 v43, v48
	s_movk_i32 s4, 0x100
	s_movk_i32 s6, 0xff
	v_add_u32_sdwa v43, v43, v44 dst_sel:DWORD dst_unused:UNUSED_PAD src0_sel:WORD_1 src1_sel:DWORD
	v_cmp_gt_i32_e64 s[4:5], s4, v43
	v_cmp_lt_i32_e64 s[6:7], s6, v43
	s_and_saveexec_b64 s[28:29], s[6:7]
	v_sub_u32_e32 v43, 0x100, v44
	v_add_u32_e32 v45, 0xc000, v138
	ds_write2_b32 v45, v100, v43 offset0:80 offset1:96
	v_mov_b32_e32 v43, v44
	s_or_b64 exec, exec, s[28:29]
	s_and_b64 exec, exec, s[4:5]
	s_cbranch_execz .LBB0_457
	v_mov_b32_e32 v44, v48
	s_movk_i32 s4, 0xff
	v_add_u32_sdwa v44, v44, v43 dst_sel:DWORD dst_unused:UNUSED_PAD src0_sel:WORD_0 src1_sel:DWORD
	v_cmp_lt_i32_e64 s[4:5], s4, v44
	s_and_b64 exec, exec, s[4:5]
	v_sub_u32_e32 v43, 0x100, v43
	v_add_u32_e32 v44, 0xc000, v138
	ds_write2_b32 v44, v99, v43 offset0:80 offset1:96

; DI void idx_scan(const u32* hq, int need, u32* outbin, u32* outneed, int q, int lane) {
;   u32 c = 0;
; #pragma unroll
;   for (int w = 0; w < 8; ++w) { u32 v = hq[8 * lane + w]; c += (v & 0xffffu) + (v >> 16); }
;   u32 incl = c;
; #pragma unroll
;   for (int o = 1; o < 64; o <<= 1) { u32 v = __shfl_down(incl, o); if (lane + o < 64) incl += v; }
;   const u32 above = incl - c;
;   if ((int)above < need && need <= (int)incl) {
;     u32 cum = above;
;     ...
;       u32 cnt = (hq[bin >> 1] >> ((bin & 1) * 16)) & 0xffffu;
;       if ((int)(cum + cnt) >= need) { outbin[q] = (u32)bin; outneed[q] = (u32)need - cum; break; }
;       cum += cnt;
;     }
;   }
; DI void idx_job(const Params& p, int b, int qg, unsigned char* smem) {
;     ...
;   for (int qq = 0; qq < 4; ++qq) idx_scan(hist + (wave * 4 + qq) * 512, (int)needB[wave * 4 + qq], binB, needC, wave * 4 + qq, lane);
.LBB0_641:
	s_or_b64 exec, exec, s[2:3]
	s_waitcnt lgkmcnt(0)
	s_barrier
	s_waitcnt vmcnt(1)
	ds_read_b128 v[42:45], v139
	s_waitcnt vmcnt(0)
	ds_read_b128 v[46:49], v139 offset:16
	s_waitcnt lgkmcnt(1)
	v_add_u32_sdwa v42, v42, v42 dst_sel:DWORD dst_unused:UNUSED_PAD src0_sel:WORD_1 src1_sel:WORD_0
	v_and_b32_e32 v50, 0xffff, v43
	v_lshrrev_b32_e32 v43, 16, v43
	v_add3_u32 v42, v42, v43, v50
	v_and_b32_e32 v43, 0xffff, v44
	v_lshrrev_b32_e32 v44, 16, v44
	v_add3_u32 v42, v42, v44, v43
	v_and_b32_e32 v43, 0xffff, v45
	v_lshrrev_b32_e32 v44, 16, v45
	v_add3_u32 v42, v42, v44, v43
	s_waitcnt lgkmcnt(0)
	v_and_b32_e32 v43, 0xffff, v46
	v_lshrrev_b32_e32 v44, 16, v46
	v_add3_u32 v42, v42, v44, v43
	v_and_b32_e32 v43, 0xffff, v47
	v_lshrrev_b32_e32 v44, 16, v47
	v_add3_u32 v42, v42, v44, v43
	v_and_b32_e32 v43, 0xffff, v48
	v_lshrrev_b32_e32 v44, 16, v48
	v_add3_u32 v42, v42, v44, v43
	v_and_b32_e32 v43, 0xffff, v49
	v_lshrrev_b32_e32 v44, 16, v49
	v_add3_u32 v43, v42, v44, v43
	ds_bpermute_b32 v42, v130, v43
	s_waitcnt lgkmcnt(0)
	v_cndmask_b32_e64 v42, v42, 0, s[40:41]
	v_add_u32_e32 v42, v43, v42
	ds_bpermute_b32 v44, v131, v42
	s_waitcnt lgkmcnt(0)
	v_cndmask_b32_e64 v44, 0, v44, s[42:43]
	v_add_u32_e32 v42, v42, v44
	ds_bpermute_b32 v44, v132, v42
	s_waitcnt lgkmcnt(0)
	v_cndmask_b32_e64 v44, 0, v44, s[44:45]
	v_add_u32_e32 v42, v42, v44
	ds_bpermute_b32 v44, v133, v42
	s_waitcnt lgkmcnt(0)
	v_cndmask_b32_e64 v44, 0, v44, s[46:47]
	v_add_u32_e32 v42, v42, v44
	ds_bpermute_b32 v44, v135, v42
	s_waitcnt lgkmcnt(0)
	v_cndmask_b32_e64 v44, 0, v44, s[48:49]
	v_add_u32_e32 v44, v42, v44
	ds_bpermute_b32 v45, v134, v44
	ds_read_b32 v42, v138 offset:49536
	s_waitcnt lgkmcnt(1)
	v_cndmask_b32_e64 v45, 0, v45, s[50:51]
	v_add_u32_e32 v45, v44, v45
	v_sub_u32_e32 v44, v45, v43
	s_waitcnt lgkmcnt(0)
	v_cmp_gt_i32_e64 s[4:5], v42, v44
	v_cmp_le_i32_e64 s[6:7], v42, v45
	s_and_b64 s[4:5], s[6:7], s[4:5]
	s_and_saveexec_b64 s[2:3], s[4:5]
	s_cbranch_execz .LBB0_690
	ds_read_b128 v[168:171], v139
	ds_read_b128 v[172:175], v139 offset:16
	s_waitcnt lgkmcnt(0)
	v_mov_b32_e32 v43, v175
	v_add_u32_sdwa v43, v43, v44 dst_sel:DWORD dst_unused:UNUSED_PAD src0_sel:WORD_1 src1_sel:DWORD
	v_cmp_lt_i32_e64 s[4:5], v43, v42
	v_cmp_ge_i32_e64 s[6:7], v43, v42
	s_and_saveexec_b64 s[8:9], s[6:7]
	v_sub_u32_e32 v43, v42, v44
	v_add_u32_e32 v45, 0xc000, v138
	ds_write2_b32 v45, v129, v43 offset0:112 offset1:128
	v_mov_b32_e32 v43, v44
	s_or_b64 exec, exec, s[8:9]
	s_and_saveexec_b64 s[6:7], s[4:5]
	s_xor_b64 s[6:7], exec, s[6:7]
	s_cbranch_execz .LBB0_690
	v_lshl_add_u32 v44, v128, 2, v140
	v_mov_b32_e32 v44, v175
	v_add_u32_sdwa v44, v44, v43 dst_sel:DWORD dst_unused:UNUSED_PAD src0_sel:WORD_0 src1_sel:DWORD
	v_cmp_lt_i32_e64 s[4:5], v44, v42
	v_cmp_ge_i32_e64 s[6:7], v44, v42
	s_and_saveexec_b64 s[8:9], s[6:7]
	v_sub_u32_e32 v44, v42, v43
	v_add_u32_e32 v45, 0xc000, v138
	ds_write2_b32 v45, v127, v44 offset0:112 offset1:128
	v_mov_b32_e32 v44, v43
	s_or_b64 exec, exec, s[8:9]
	s_and_saveexec_b64 s[8:9], s[4:5]
	s_cbranch_execz .LBB0_689
	v_lshl_add_u32 v43, v126, 2, v140
	v_mov_b32_e32 v43, v174
	v_add_u32_sdwa v43, v43, v44 dst_sel:DWORD dst_unused:UNUSED_PAD src0_sel:WORD_1 src1_sel:DWORD
	v_cmp_lt_i32_e64 s[4:5], v43, v42
	v_cmp_ge_i32_e64 s[6:7], v43, v42
	s_and_saveexec_b64 s[28:29], s[6:7]
	v_sub_u32_e32 v43, v42, v44
	v_add_u32_e32 v45, 0xc000, v138
	ds_write2_b32 v45, v125, v43 offset0:112 offset1:128
	v_mov_b32_e32 v43, v44
	s_or_b64 exec, exec, s[28:29]
	s_and_b64 exec, exec, s[4:5]
	s_cbranch_execz .LBB0_689
	v_lshl_add_u32 v44, v122, 2, v140
	v_mov_b32_e32 v44, v174
	v_add_u32_sdwa v44, v44, v43 dst_sel:DWORD dst_unused:UNUSED_PAD src0_sel:WORD_0 src1_sel:DWORD
	v_cmp_lt_i32_e64 s[4:5], v44, v42
	v_cmp_ge_i32_e64 s[6:7], v44, v42
	s_and_saveexec_b64 s[28:29], s[6:7]
	v_sub_u32_e32 v44, v42, v43
	v_add_u32_e32 v45, 0xc000, v138
	ds_write2_b32 v45, v120, v44 offset0:112 offset1:128
	v_mov_b32_e32 v44, v43
	s_or_b64 exec, exec, s[28:29]
	s_and_b64 exec, exec, s[4:5]
	s_cbranch_execz .LBB0_689
	v_lshl_add_u32 v43, v123, 2, v140
	v_mov_b32_e32 v43, v173
	v_add_u32_sdwa v43, v43, v44 dst_sel:DWORD dst_unused:UNUSED_PAD src0_sel:WORD_1 src1_sel:DWORD
	v_cmp_lt_i32_e64 s[4:5], v43, v42
	v_cmp_ge_i32_e64 s[6:7], v43, v42
	s_and_saveexec_b64 s[28:29], s[6:7]
	v_sub_u32_e32 v43, v42, v44
	v_add_u32_e32 v45, 0xc000, v138
	ds_write2_b32 v45, v121, v43 offset0:112 offset1:128
	v_mov_b32_e32 v43, v44
	s_or_b64 exec, exec, s[28:29]
	s_and_b64 exec, exec, s[4:5]
	s_cbranch_execz .LBB0_689
	v_lshl_add_u32 v44, v124, 2, v140
	v_mov_b32_e32 v44, v173
	v_add_u32_sdwa v44, v44, v43 dst_sel:DWORD dst_unused:UNUSED_PAD src0_sel:WORD_0 src1_sel:DWORD
	v_cmp_lt_i32_e64 s[4:5], v44, v42
	v_cmp_ge_i32_e64 s[6:7], v44, v42
	s_and_saveexec_b64 s[28:29], s[6:7]
	v_sub_u32_e32 v44, v42, v43
	v_add_u32_e32 v45, 0xc000, v138
	ds_write2_b32 v45, v117, v44 offset0:112 offset1:128
	v_mov_b32_e32 v44, v43
	s_or_b64 exec, exec, s[28:29]
	s_and_b64 exec, exec, s[4:5]
	s_cbranch_execz .LBB0_689
; DI void idx_scan(const u32* hq, int need, u32* outbin, u32* outneed, int q, int lane) {
;     ...
;   if ((int)above < need && need <= (int)incl) {
;     u32 cum = above;
;     ...
;       u32 cnt = (hq[bin >> 1] >> ((bin & 1) * 16)) & 0xffffu;
;       if ((int)(cum + cnt) >= need) { outbin[q] = (u32)bin; outneed[q] = (u32)need - cum; break; }
;       cum += cnt;
;     }
;   }
	v_lshl_add_u32 v43, v119, 2, v140
	v_mov_b32_e32 v43, v172
	v_add_u32_sdwa v43, v43, v44 dst_sel:DWORD dst_unused:UNUSED_PAD src0_sel:WORD_1 src1_sel:DWORD
	v_cmp_lt_i32_e64 s[4:5], v43, v42
	v_cmp_ge_i32_e64 s[6:7], v43, v42
	s_and_saveexec_b64 s[28:29], s[6:7]
	v_sub_u32_e32 v43, v42, v44
	v_add_u32_e32 v45, 0xc000, v138
	ds_write2_b32 v45, v118, v43 offset0:112 offset1:128
	v_mov_b32_e32 v43, v44
	s_or_b64 exec, exec, s[28:29]
	s_and_b64 exec, exec, s[4:5]
	s_cbranch_execz .LBB0_689
	v_lshl_add_u32 v44, v116, 2, v140
	v_mov_b32_e32 v44, v172
	v_add_u32_sdwa v44, v44, v43 dst_sel:DWORD dst_unused:UNUSED_PAD src0_sel:WORD_0 src1_sel:DWORD
	v_cmp_lt_i32_e64 s[4:5], v44, v42
	v_cmp_ge_i32_e64 s[6:7], v44, v42
	s_and_saveexec_b64 s[28:29], s[6:7]
	v_sub_u32_e32 v44, v42, v43
	v_add_u32_e32 v45, 0xc000, v138
	ds_write2_b32 v45, v115, v44 offset0:112 offset1:128
	v_mov_b32_e32 v44, v43
	s_or_b64 exec, exec, s[28:29]
	s_and_b64 exec, exec, s[4:5]
	s_cbranch_execz .LBB0_689
	v_lshl_add_u32 v43, v114, 2, v140
	v_mov_b32_e32 v43, v171
	v_add_u32_sdwa v43, v43, v44 dst_sel:DWORD dst_unused:UNUSED_PAD src0_sel:WORD_1 src1_sel:DWORD
	v_cmp_lt_i32_e64 s[4:5], v43, v42
	v_cmp_ge_i32_e64 s[6:7], v43, v42
	s_and_saveexec_b64 s[28:29], s[6:7]
	v_sub_u32_e32 v43, v42, v44
	v_add_u32_e32 v45, 0xc000, v138
	ds_write2_b32 v45, v113, v43 offset0:112 offset1:128
	v_mov_b32_e32 v43, v44
	s_or_b64 exec, exec, s[28:29]
	s_and_b64 exec, exec, s[4:5]
	s_cbranch_execz .LBB0_689
	v_lshl_add_u32 v44, v112, 2, v140
	v_mov_b32_e32 v44, v171
	v_add_u32_sdwa v44, v44, v43 dst_sel:DWORD dst_unused:UNUSED_PAD src0_sel:WORD_0 src1_sel:DWORD
	v_cmp_lt_i32_e64 s[4:5], v44, v42
	v_cmp_ge_i32_e64 s[6:7], v44, v42
	s_and_saveexec_b64 s[28:29], s[6:7]
	v_sub_u32_e32 v44, v42, v43
	v_add_u32_e32 v45, 0xc000, v138
	ds_write2_b32 v45, v111, v44 offset0:112 offset1:128
	v_mov_b32_e32 v44, v43
	s_or_b64 exec, exec, s[28:29]
	s_and_b64 exec, exec, s[4:5]
	s_cbranch_execz .LBB0_689
	v_lshl_add_u32 v43, v110, 2, v140
	v_mov_b32_e32 v43, v170
	v_add_u32_sdwa v43, v43, v44 dst_sel:DWORD dst_unused:UNUSED_PAD src0_sel:WORD_1 src1_sel:DWORD
	v_cmp_lt_i32_e64 s[4:5], v43, v42
	v_cmp_ge_i32_e64 s[6:7], v43, v42
	s_and_saveexec_b64 s[28:29], s[6:7]
	v_sub_u32_e32 v43, v42, v44
	v_add_u32_e32 v45, 0xc000, v138
	ds_write2_b32 v45, v107, v43 offset0:112 offset1:128
	v_mov_b32_e32 v43, v44
	s_or_b64 exec, exec, s[28:29]
	s_and_b64 exec, exec, s[4:5]
	s_cbranch_execz .LBB0_689
	v_lshl_add_u32 v44, v106, 2, v140
	v_mov_b32_e32 v44, v170
	v_add_u32_sdwa v44, v44, v43 dst_sel:DWORD dst_unused:UNUSED_PAD src0_sel:WORD_0 src1_sel:DWORD
	v_cmp_lt_i32_e64 s[4:5], v44, v42
	v_cmp_ge_i32_e64 s[6:7], v44, v42
	s_and_saveexec_b64 s[28:29], s[6:7]
	v_sub_u32_e32 v44, v42, v43
	v_add_u32_e32 v45, 0xc000, v138
	ds_write2_b32 v45, v105, v44 offset0:112 offset1:128
	v_mov_b32_e32 v44, v43
	s_or_b64 exec, exec, s[28:29]
	s_and_b64 exec, exec, s[4:5]
	s_cbranch_execz .LBB0_689
	v_lshl_add_u32 v43, v104, 2, v140
	v_mov_b32_e32 v43, v169
	v_add_u32_sdwa v43, v43, v44 dst_sel:DWORD dst_unused:UNUSED_PAD src0_sel:WORD_1 src1_sel:DWORD
	v_cmp_lt_i32_e64 s[4:5], v43, v42
	v_cmp_ge_i32_e64 s[6:7], v43, v42
	s_and_saveexec_b64 s[28:29], s[6:7]
	v_sub_u32_e32 v43, v42, v44
	v_add_u32_e32 v45, 0xc000, v138
	ds_write2_b32 v45, v103, v43 offset0:112 offset1:128
	v_mov_b32_e32 v43, v44
	s_or_b64 exec, exec, s[28:29]
	s_and_b64 exec, exec, s[4:5]
	s_cbranch_execz .LBB0_689
	v_lshl_add_u32 v44, v102, 2, v140
	v_mov_b32_e32 v44, v169
	v_add_u32_sdwa v44, v44, v43 dst_sel:DWORD dst_unused:UNUSED_PAD src0_sel:WORD_0 src1_sel:DWORD
	v_cmp_lt_i32_e64 s[4:5], v44, v42
	v_cmp_ge_i32_e64 s[6:7], v44, v42
	s_and_saveexec_b64 s[28:29], s[6:7]
	v_sub_u32_e32 v44, v42, v43
	v_add_u32_e32 v45, 0xc000, v138
	ds_write2_b32 v45, v101, v44 offset0:112 offset1:128
	v_mov_b32_e32 v44, v43
	s_or_b64 exec, exec, s[28:29]
	s_and_b64 exec, exec, s[4:5]
	s_cbranch_execz .LBB0_689
	v_mov_b32_e32 v43, v168
	v_add_u32_sdwa v43, v43, v44 dst_sel:DWORD dst_unused:UNUSED_PAD src0_sel:WORD_1 src1_sel:DWORD
	v_cmp_lt_i32_e64 s[4:5], v43, v42
	v_cmp_ge_i32_e64 s[6:7], v43, v42
	s_and_saveexec_b64 s[28:29], s[6:7]
	v_sub_u32_e32 v43, v42, v44
	v_add_u32_e32 v45, 0xc000, v138
	ds_write2_b32 v45, v100, v43 offset0:112 offset1:128
	v_mov_b32_e32 v43, v44
	s_or_b64 exec, exec, s[28:29]
	s_and_b64 exec, exec, s[4:5]
	s_cbranch_execz .LBB0_689
	v_mov_b32_e32 v44, v168
	v_add_u32_sdwa v44, v44, v43 dst_sel:DWORD dst_unused:UNUSED_PAD src0_sel:WORD_0 src1_sel:DWORD
	v_cmp_ge_i32_e64 s[4:5], v44, v42
	s_and_b64 exec, exec, s[4:5]
	v_sub_u32_e32 v42, v42, v43
	v_add_u32_e32 v43, 0xc000, v138
	ds_write2_b32 v43, v99, v42 offset0:112 offset1:128
